# v047 with the P3 static priority raise at level 1 instead of 2
# baseline (speedup 1.0000x reference)
; __device__ __forceinline__ void xcd_barrier(unsigned* bar, volatile LAS unsigned* st, bool leader, unsigned G) {
;     ...
;     __syncthreads();
; __global__ void __launch_bounds__(512, 2) hybrid_fwd(Params p) {
;     ...
;         if (PH(3)) { PHB
;             if (c < 128) {
;                 const int u = c;
;                     const int qb = 31 - (u >> 2), hd = u & 3, tq0 = 256 * qb + 32 * wave, t_row = tq0 + (lane & 31);
.LBB0_533:
	s_or_b64 exec, exec, s[0:1]
	v_readlane_b32 s0, v255, 0
	s_mov_b32 s70, s23
	s_mov_b32 s2, s0
	v_mov_b32_e32 v144, v234
	s_waitcnt lgkmcnt(0)
	s_barrier
	s_mov_b64 s[8:9], s[50:51]
	v_readfirstlane_b32 s15, v144
	s_ashr_i32 s3, s15, 6
	s_cmp_lt_u32 s3, 4
	s_cbranch_scc0 .Lp3_prio_skip
	s_setprio 1
